# LayerNorm first row loop: residual row prefetched two rows ahead (row loop unrolled by two, prefetch alternating between two register sets) to double the bytes in flight
# baseline (speedup 1.0000x reference)
.LBB0_1620:
	s_andn2_b64 vcc, exec, s[2:3]
	s_cbranch_vccnz .LBB0_1693
	v_readlane_b32 s0, v251, 52
	s_mov_b32 s1, s80
	v_mbcnt_lo_u32_b32 v0, -1, 0
	v_mbcnt_hi_u32_b32 v0, -1, v0
	s_nop 0
	v_readlane_b32 s1, v253, 48
	s_add_i32 s6, s0, s1
	s_cmpk_gt_i32 s6, 0x7fff
	s_cbranch_scc1 .LBB0_1626
	s_ashr_i32 s7, s6, 31
	s_lshl_b64 s[0:1], s[6:7], 12
	v_lshlrev_b32_e32 v2, 2, v0
	s_add_u32 s0, s90, s0
	v_ashrrev_i32_e32 v3, 31, v2
	s_addc_u32 s1, s91, s1
	v_lshlrev_b64 v[16:17], 2, v[2:3]
	s_waitcnt vmcnt(0)
	v_lshl_add_u64 v[12:13], s[0:1], 0, v[16:17]
	global_load_dwordx4 v[20:23], v[12:13], off
	global_load_dwordx4 v[8:11], v[12:13], off offset:1024
	global_load_dwordx4 v[4:7], v[12:13], off offset:2048
	s_nop 0
	global_load_dwordx4 v[12:15], v[12:13], off offset:3072
	v_readlane_b32 s0, v254, 58
	v_readlane_b32 s1, v254, 59
	v_lshl_add_u64 v[24:25], s[90:91], 0, v[16:17]
	v_cmp_eq_u32_e64 s[38:39], 0, v0
	s_waitcnt vmcnt(0)
	v_lshl_add_u64 v[26:27], s[0:1], 0, v[16:17]
	v_readlane_b32 s0, v254, 60
	v_readlane_b32 s1, v254, 61
	v_lshl_add_u64 v[30:31], s[92:93], 0, v[16:17]
	v_mov_b32_e32 v39, v20
	v_lshl_add_u64 v[28:29], s[0:1], 0, v[16:17]
	s_lshl_b64 s[0:1], s[6:7], 11
	v_lshl_add_u64 v[32:33], v[2:3], 1, s[0:1]
	s_lshl_b64 s[0:1], s[6:7], 3
	s_add_u32 s0, s0, 0x15c00000
	s_addc_u32 s1, s1, 0
	v_mov_b32_e32 v41, v22
	v_mov_b32_e32 v38, v8
	v_mov_b32_e32 v20, v9
	v_mov_b32_e32 v40, v10
	v_mov_b32_e32 v22, v11
	v_mov_b32_e32 v35, v4
	v_mov_b32_e32 v37, v6
	v_mov_b32_e32 v34, v12
	v_mov_b32_e32 v4, v13
	v_mov_b32_e32 v36, v14
	v_mov_b32_e32 v6, v15
	s_add_i32 s100, s6, s82
	s_cmp_lt_i32 s100, 0x8000
	s_cselect_b32 s100, s100, s6
	s_ashr_i32 s101, s100, 31
	s_lshl_b64 s[100:101], s[100:101], 12
	v_lshl_add_u64 v[176:177], v[24:25], 0, s[100:101]
	global_load_dwordx4 v[16:19], v[176:177], off
	global_load_dwordx4 v[12:15], v[176:177], off offset:1024
	global_load_dwordx4 v[8:11], v[176:177], off offset:2048
	global_load_dwordx4 v[0:3], v[176:177], off offset:3072
	s_branch .LBB0_1624
.LBB0_1623:
	s_or_b64 exec, exec, s[12:13]
	s_waitcnt vmcnt(5)
	v_mov_b32_e32 v46, v39
	v_mov_b32_e32 v47, v21
	v_mov_b32_e32 v39, v20
	v_pk_mul_f32 v[20:21], v[46:47], v[42:43] op_sel_hi:[1,0]
	s_add_i32 s11, s6, 0xffffc000
	s_lshr_b32 s11, s11, 12
	s_ashr_i32 s10, s6, 13
	s_add_i32 s11, s11, 2
	s_cmpk_lt_i32 s6, 0x4000
	s_cselect_b32 s6, s10, s11
	v_readlane_b32 s8, v255, 11
	s_add_i32 s6, s6, s8
	s_mul_i32 s10, s6, 9
	v_mov_b32_e32 v44, v35
	v_mov_b32_e32 v45, v5
	v_mov_b32_e32 v35, v4
	s_ashr_i32 s11, s10, 31
	v_mov_b32_e32 v4, v41
	v_mov_b32_e32 v5, v23
	s_lshl_b64 s[10:11], s[10:11], 12
	v_pk_mul_f32 v[4:5], v[4:5], v[42:43] op_sel_hi:[1,0]
	s_movk_i32 s6, 0x7000
	v_mov_b32_e32 v41, v22
	v_pk_mul_f32 v[22:23], v[40:41], v[42:43] op_sel_hi:[1,0]
	v_pk_mul_f32 v[44:45], v[44:45], v[42:43] op_sel_hi:[1,0]
	v_readlane_b32 s8, v254, 12
	v_readlane_b32 s9, v254, 13
	v_pk_fma_f32 v[56:57], v[4:5], v[70:71], v[74:75]
	v_lshl_add_u64 v[4:5], v[30:31], 0, s[10:11]
	v_pk_fma_f32 v[58:59], v[20:21], v[68:69], v[72:73]
	v_add_co_u32_e32 v52, vcc, s6, v4
	s_mov_b32 s6, 0x2c00000
	s_nop 0
	v_addc_co_u32_e32 v53, vcc, 0, v5, vcc
	s_mov_b64 s[10:11], 0x6000
	v_lshl_add_u64 v[20:21], v[4:5], 0, s[10:11]
	s_mov_b64 s[10:11], 0x7000
	v_lshl_add_u64 v[4:5], v[4:5], 0, s[10:11]
	v_pk_add_f32 v[52:53], v[80:81], 1.0 op_sel_hi:[1,0]
	s_nop 0
	v_pk_fma_f32 v[46:47], v[58:59], v[52:53], v[76:77]
	v_pk_add_f32 v[54:55], v[82:83], 1.0 op_sel_hi:[1,0]
	v_cvt_pk_bf16_f32 v52, v46, v47
	v_lshl_add_u64 v[46:47], s[92:93], 0, v[32:33]
	v_add_co_u32_e32 v46, vcc, s6, v46
	v_pk_fma_f32 v[48:49], v[56:57], v[54:55], v[78:79]
	s_nop 0
	v_addc_co_u32_e32 v47, vcc, 0, v47, vcc
	v_cvt_pk_bf16_f32 v53, v48, v49
	global_store_dwordx2 v[46:47], v[52:53], off
	v_pk_mul_f32 v[48:49], v[38:39], v[42:43] op_sel_hi:[1,0]
	v_lshl_add_u64 v[32:33], v[32:33], 0, s[8:9]
	v_readlane_b32 s8, v254, 14
	v_readlane_b32 s9, v254, 15
	s_add_u32 s0, s0, s8
	s_addc_u32 s1, s1, s9
	s_andn2_b64 vcc, exec, s[2:3]
	s_mov_b32 s6, s7
	v_pk_fma_f32 v[22:23], v[22:23], v[86:87], v[90:91]
	v_pk_fma_f32 v[48:49], v[48:49], v[84:85], v[88:89]
	v_pk_add_f32 v[52:53], v[96:97], 1.0 op_sel_hi:[1,0]
	v_pk_add_f32 v[54:55], v[98:99], 1.0 op_sel_hi:[1,0]
	v_pk_fma_f32 v[38:39], v[48:49], v[52:53], v[92:93]
	v_pk_fma_f32 v[22:23], v[22:23], v[54:55], v[94:95]
	v_cvt_pk_bf16_f32 v38, v38, v39
	s_nop 0
	v_cvt_pk_bf16_f32 v39, v22, v23
	global_store_dwordx2 v[46:47], v[38:39], off offset:512
	s_nop 0
	v_mov_b32_e32 v22, v37
	v_mov_b32_e32 v23, v7
	v_pk_mul_f32 v[22:23], v[22:23], v[42:43] op_sel_hi:[1,0]
	v_mov_b32_e32 v37, v6
	v_pk_mul_f32 v[6:7], v[36:37], v[42:43] op_sel_hi:[1,0]
	v_pk_fma_f32 v[22:23], v[22:23], v[102:103], v[106:107]
	v_pk_fma_f32 v[44:45], v[44:45], v[100:101], v[104:105]
	v_pk_add_f32 v[52:53], v[112:113], 1.0 op_sel_hi:[1,0]
	v_pk_add_f32 v[48:49], v[114:115], 1.0 op_sel_hi:[1,0]
	v_pk_fma_f32 v[38:39], v[44:45], v[52:53], v[108:109]
	v_pk_fma_f32 v[22:23], v[22:23], v[48:49], v[110:111]
	v_cvt_pk_bf16_f32 v38, v38, v39
	s_nop 0
	v_cvt_pk_bf16_f32 v39, v22, v23
	global_store_dwordx2 v[46:47], v[38:39], off offset:1024
	v_pk_mul_f32 v[22:23], v[34:35], v[42:43] op_sel_hi:[1,0]
	v_pk_fma_f32 v[36:37], v[6:7], v[118:119], v[122:123]
	v_pk_fma_f32 v[34:35], v[22:23], v[116:117], v[120:121]
	s_nop 0
	s_waitcnt vmcnt(8)
	v_mov_b32_e32 v39, v16
	v_mov_b32_e32 v41, v18
	v_mov_b32_e32 v38, v12
	v_mov_b32_e32 v40, v14
	v_pk_add_f32 v[4:5], v[128:129], 1.0 op_sel_hi:[1,0]
	v_pk_add_f32 v[6:7], v[130:131], 1.0 op_sel_hi:[1,0]
	v_pk_fma_f32 v[4:5], v[34:35], v[4:5], v[124:125]
	v_pk_fma_f32 v[6:7], v[36:37], v[6:7], v[126:127]
	v_cvt_pk_bf16_f32 v4, v4, v5
	v_mov_b32_e32 v21, v17
	v_cvt_pk_bf16_f32 v5, v6, v7
	global_store_dwordx2 v[46:47], v[4:5], off offset:1536
	v_mov_b32_e32 v23, v19
	v_mov_b32_e32 v20, v13
	v_mov_b32_e32 v22, v15
	v_mov_b32_e32 v35, v8
	v_mov_b32_e32 v5, v9
	v_mov_b32_e32 v37, v10
	v_mov_b32_e32 v7, v11
	v_mov_b32_e32 v34, v0
	v_mov_b32_e32 v4, v1
	v_mov_b32_e32 v36, v2
	v_mov_b32_e32 v6, v3
	s_cbranch_vccz .Lln2a_exit
	s_branch .Lln2a_topB
.LBB0_1624:
	s_add_i32 s7, s6, s82
	s_cmpk_gt_i32 s7, 0x7fff
	s_cselect_b64 s[2:3], -1, 0
	s_add_i32 s10, s7, s82
	s_cmp_lt_i32 s10, 0x8000
	s_cselect_b32 s10, s10, s6
	s_ashr_i32 s11, s10, 31
	s_lshl_b64 s[10:11], s[10:11], 12
	v_lshl_add_u64 v[176:177], v[24:25], 0, s[10:11]
	s_add_i32 s101, s6, 0xffffc000
	s_lshr_b32 s101, s101, 12
	s_add_i32 s101, s101, 2
	s_ashr_i32 s100, s6, 13
	s_cmpk_lt_i32 s6, 0x4000
	s_cselect_b32 s100, s100, s101
	v_readlane_b32 s101, v255, 11
	s_nop 1
	s_add_i32 s100, s100, s101
	s_mul_i32 s100, s100, 9
	s_ashr_i32 s101, s100, 31
	s_lshl_b64 s[100:101], s[100:101], 12
	v_lshl_add_u64 v[60:61], v[30:31], 0, s[100:101]
	s_mov_b64 s[100:101], 0x6000
	v_lshl_add_u64 v[62:63], v[60:61], 0, s[100:101]
	s_mov_b64 s[100:101], 0x7000
	v_lshl_add_u64 v[64:65], v[60:61], 0, s[100:101]
	global_load_dwordx4 v[68:71], v[26:27], off
	global_load_dwordx4 v[72:75], v[28:29], off
	global_load_dwordx4 v[76:79], v[62:63], off
	global_load_dwordx4 v[80:83], v[64:65], off
	global_load_dwordx4 v[84:87], v[26:27], off offset:1024
	global_load_dwordx4 v[88:91], v[28:29], off offset:1024
	global_load_dwordx4 v[92:95], v[62:63], off offset:1024
	global_load_dwordx4 v[96:99], v[64:65], off offset:1024
	global_load_dwordx4 v[100:103], v[26:27], off offset:2048
	global_load_dwordx4 v[104:107], v[28:29], off offset:2048
	global_load_dwordx4 v[108:111], v[62:63], off offset:2048
	global_load_dwordx4 v[112:115], v[64:65], off offset:2048
	global_load_dwordx4 v[116:119], v[26:27], off offset:3072
	global_load_dwordx4 v[120:123], v[28:29], off offset:3072
	global_load_dwordx4 v[124:127], v[62:63], off offset:3072
	global_load_dwordx4 v[128:131], v[64:65], off offset:3072
	global_load_dwordx4 v[164:167], v[176:177], off
	global_load_dwordx4 v[168:171], v[176:177], off offset:1024
	global_load_dwordx4 v[172:175], v[176:177], off offset:2048
	s_nop 0
	global_load_dwordx4 v[176:179], v[176:177], off offset:3072
	v_pk_add_f32 v[42:43], v[38:39], v[20:21]
	s_mov_b32 s8, 0x800000
	v_pk_add_f32 v[42:43], v[40:41], v[42:43]
	s_nop 0
	v_pk_add_f32 v[42:43], v[22:23], v[42:43]
	s_nop 0
	v_add_f32_e32 v43, 0, v43
	v_add_f32_e32 v44, v42, v43
	v_pk_add_f32 v[42:43], v[34:35], v[4:5]
	s_nop 0
	v_pk_add_f32 v[42:43], v[36:37], v[42:43]
	s_nop 0
	v_pk_add_f32 v[42:43], v[6:7], v[42:43]
	s_nop 0
	v_add_f32_e32 v43, v43, v44
	v_add_f32_e32 v42, v42, v43
	s_nop 1
	v_add_f32_dpp v42, v42, v42 quad_perm:[1,0,3,2] row_mask:0xf bank_mask:0xf bound_ctrl:1
	s_nop 1
	v_add_f32_dpp v42, v42, v42 quad_perm:[2,3,0,1] row_mask:0xf bank_mask:0xf bound_ctrl:1
	s_nop 1
	v_add_f32_dpp v42, v42, v42 row_half_mirror row_mask:0xf bank_mask:0xf bound_ctrl:1
	s_nop 1
	v_add_f32_dpp v42, v42, v42 row_mirror row_mask:0xf bank_mask:0xf bound_ctrl:1
	s_nop 0
	v_readlane_b32 s12, v42, 16
	v_readlane_b32 s13, v42, 48
	v_readlane_b32 s10, v42, 0
	v_readlane_b32 s11, v42, 32
	v_mov_b32_e32 v42, s12
	v_mov_b32_e32 v43, s13
	v_pk_add_f32 v[42:43], s[10:11], v[42:43]
	s_nop 0
	v_add_f32_e32 v43, v42, v43
	v_fmac_f32_e32 v21, 0xba800000, v43
	v_fmac_f32_e32 v20, 0xba800000, v43
	v_fmac_f32_e32 v39, 0xba800000, v43
	v_fmac_f32_e32 v38, 0xba800000, v43
	v_mov_b32_e32 v46, v21
	v_mov_b32_e32 v47, v20
	v_fmac_f32_e32 v41, 0xba800000, v43
	v_fmac_f32_e32 v40, 0xba800000, v43
	v_mov_b32_e32 v44, v39
	v_mov_b32_e32 v45, v38
	v_pk_mul_f32 v[46:47], v[46:47], v[46:47]
	v_fmac_f32_e32 v23, 0xba800000, v43
	v_fmac_f32_e32 v22, 0xba800000, v43
	v_pk_fma_f32 v[44:45], v[44:45], v[44:45], v[46:47]
	v_mov_b32_e32 v46, v41
	v_mov_b32_e32 v47, v40
	v_pk_fma_f32 v[44:45], v[46:47], v[46:47], v[44:45]
	v_mov_b32_e32 v46, v23
	v_mov_b32_e32 v47, v22
	v_fmac_f32_e32 v5, 0xba800000, v43
	v_fmac_f32_e32 v4, 0xba800000, v43
	v_pk_fma_f32 v[44:45], v[46:47], v[46:47], v[44:45]
	v_fmac_f32_e32 v35, 0xba800000, v43
	v_fmac_f32_e32 v34, 0xba800000, v43
	v_pk_mul_f32 v[46:47], v[4:5], v[4:5]
	v_fmac_f32_e32 v37, 0xba800000, v43
	v_fmac_f32_e32 v36, 0xba800000, v43
	v_pk_fma_f32 v[46:47], v[34:35], v[34:35], v[46:47]
	v_fmac_f32_e32 v7, 0xba800000, v43
	v_fmac_f32_e32 v6, 0xba800000, v43
	v_pk_fma_f32 v[46:47], v[36:37], v[36:37], v[46:47]
	v_add_f32_e32 v42, v44, v45
	v_pk_fma_f32 v[46:47], v[6:7], v[6:7], v[46:47]
	s_nop 0
	v_add_f32_e32 v42, v47, v42
	v_add_f32_e32 v42, v46, v42
	s_nop 1
	v_add_f32_dpp v42, v42, v42 quad_perm:[1,0,3,2] row_mask:0xf bank_mask:0xf bound_ctrl:1
	s_nop 1
	v_add_f32_dpp v42, v42, v42 quad_perm:[2,3,0,1] row_mask:0xf bank_mask:0xf bound_ctrl:1
	s_nop 1
	v_add_f32_dpp v42, v42, v42 row_half_mirror row_mask:0xf bank_mask:0xf bound_ctrl:1
	s_nop 1
	v_add_f32_dpp v42, v42, v42 row_mirror row_mask:0xf bank_mask:0xf bound_ctrl:1
	s_nop 0
	v_readlane_b32 s12, v42, 16
	v_readlane_b32 s13, v42, 48
	v_readlane_b32 s10, v42, 0
	v_readlane_b32 s11, v42, 32
	v_mov_b32_e32 v44, s12
	v_mov_b32_e32 v45, s13
	v_pk_add_f32 v[44:45], s[10:11], v[44:45]
	s_nop 0
	v_add_f32_e32 v42, v44, v45
	v_fmamk_f32 v42, v42, 0x3a800000, v232
	v_mul_f32_e32 v44, 0x4b800000, v42
	v_cmp_gt_f32_e32 vcc, s8, v42
	s_nop 1
	v_cndmask_b32_e32 v42, v42, v44, vcc
	v_rsq_f32_e32 v42, v42
	s_nop 0
	v_mul_f32_e32 v44, 0x45800000, v42
	v_cndmask_b32_e32 v42, v42, v44, vcc
	s_and_saveexec_b64 s[12:13], s[38:39]
	s_cbranch_execz .LBB0_1623
	s_add_u32 s10, s92, s0
	v_mul_f32_e32 v44, 0x3a800000, v43
	s_addc_u32 s11, s93, s1
	v_mov_b32_e32 v45, v42
	global_store_dwordx2 v51, v[44:45], s[10:11]
	s_branch .LBB0_1623
.Lln2a_outB:
	s_or_b64 exec, exec, s[12:13]
	s_waitcnt vmcnt(5)
	v_mov_b32_e32 v46, v39
	v_mov_b32_e32 v47, v21
	v_mov_b32_e32 v39, v20
	v_pk_mul_f32 v[20:21], v[46:47], v[42:43] op_sel_hi:[1,0]
	s_add_i32 s11, s6, 0xffffc000
	s_lshr_b32 s11, s11, 12
	s_ashr_i32 s10, s6, 13
	s_add_i32 s11, s11, 2
	s_cmpk_lt_i32 s6, 0x4000
	s_cselect_b32 s6, s10, s11
	v_readlane_b32 s8, v255, 11
	s_add_i32 s6, s6, s8
	s_mul_i32 s10, s6, 9
	v_mov_b32_e32 v44, v35
	v_mov_b32_e32 v45, v5
	v_mov_b32_e32 v35, v4
	s_ashr_i32 s11, s10, 31
	v_mov_b32_e32 v4, v41
	v_mov_b32_e32 v5, v23
	s_lshl_b64 s[10:11], s[10:11], 12
	v_pk_mul_f32 v[4:5], v[4:5], v[42:43] op_sel_hi:[1,0]
	s_movk_i32 s6, 0x7000
	v_mov_b32_e32 v41, v22
	v_pk_mul_f32 v[22:23], v[40:41], v[42:43] op_sel_hi:[1,0]
	v_pk_mul_f32 v[44:45], v[44:45], v[42:43] op_sel_hi:[1,0]
	v_readlane_b32 s8, v254, 12
	v_readlane_b32 s9, v254, 13
	v_pk_fma_f32 v[56:57], v[4:5], v[70:71], v[74:75]
	v_lshl_add_u64 v[4:5], v[30:31], 0, s[10:11]
	v_pk_fma_f32 v[58:59], v[20:21], v[68:69], v[72:73]
	v_add_co_u32_e32 v52, vcc, s6, v4
	s_mov_b32 s6, 0x2c00000
	s_nop 0
	v_addc_co_u32_e32 v53, vcc, 0, v5, vcc
	s_mov_b64 s[10:11], 0x6000
	v_lshl_add_u64 v[20:21], v[4:5], 0, s[10:11]
	s_mov_b64 s[10:11], 0x7000
	v_lshl_add_u64 v[4:5], v[4:5], 0, s[10:11]
	v_pk_add_f32 v[52:53], v[80:81], 1.0 op_sel_hi:[1,0]
	s_nop 0
	v_pk_fma_f32 v[46:47], v[58:59], v[52:53], v[76:77]
	v_pk_add_f32 v[54:55], v[82:83], 1.0 op_sel_hi:[1,0]
	v_cvt_pk_bf16_f32 v52, v46, v47
	v_lshl_add_u64 v[46:47], s[92:93], 0, v[32:33]
	v_add_co_u32_e32 v46, vcc, s6, v46
	v_pk_fma_f32 v[48:49], v[56:57], v[54:55], v[78:79]
	s_nop 0
	v_addc_co_u32_e32 v47, vcc, 0, v47, vcc
	v_cvt_pk_bf16_f32 v53, v48, v49
	global_store_dwordx2 v[46:47], v[52:53], off
	v_pk_mul_f32 v[48:49], v[38:39], v[42:43] op_sel_hi:[1,0]
	v_lshl_add_u64 v[32:33], v[32:33], 0, s[8:9]
	v_readlane_b32 s8, v254, 14
	v_readlane_b32 s9, v254, 15
	s_add_u32 s0, s0, s8
	s_addc_u32 s1, s1, s9
	s_andn2_b64 vcc, exec, s[2:3]
	s_mov_b32 s6, s7
	v_pk_fma_f32 v[22:23], v[22:23], v[86:87], v[90:91]
	v_pk_fma_f32 v[48:49], v[48:49], v[84:85], v[88:89]
	v_pk_add_f32 v[52:53], v[96:97], 1.0 op_sel_hi:[1,0]
	v_pk_add_f32 v[54:55], v[98:99], 1.0 op_sel_hi:[1,0]
	v_pk_fma_f32 v[38:39], v[48:49], v[52:53], v[92:93]
	v_pk_fma_f32 v[22:23], v[22:23], v[54:55], v[94:95]
	v_cvt_pk_bf16_f32 v38, v38, v39
	s_nop 0
	v_cvt_pk_bf16_f32 v39, v22, v23
	global_store_dwordx2 v[46:47], v[38:39], off offset:512
	s_nop 0
	v_mov_b32_e32 v22, v37
	v_mov_b32_e32 v23, v7
	v_pk_mul_f32 v[22:23], v[22:23], v[42:43] op_sel_hi:[1,0]
	v_mov_b32_e32 v37, v6
	v_pk_mul_f32 v[6:7], v[36:37], v[42:43] op_sel_hi:[1,0]
	v_pk_fma_f32 v[22:23], v[22:23], v[102:103], v[106:107]
	v_pk_fma_f32 v[44:45], v[44:45], v[100:101], v[104:105]
	v_pk_add_f32 v[52:53], v[112:113], 1.0 op_sel_hi:[1,0]
	v_pk_add_f32 v[48:49], v[114:115], 1.0 op_sel_hi:[1,0]
	v_pk_fma_f32 v[38:39], v[44:45], v[52:53], v[108:109]
	v_pk_fma_f32 v[22:23], v[22:23], v[48:49], v[110:111]
	v_cvt_pk_bf16_f32 v38, v38, v39
	s_nop 0
	v_cvt_pk_bf16_f32 v39, v22, v23
	global_store_dwordx2 v[46:47], v[38:39], off offset:1024
	v_pk_mul_f32 v[22:23], v[34:35], v[42:43] op_sel_hi:[1,0]
	v_pk_fma_f32 v[36:37], v[6:7], v[118:119], v[122:123]
	v_pk_fma_f32 v[34:35], v[22:23], v[116:117], v[120:121]
	s_nop 0
	s_waitcnt vmcnt(8)
	v_mov_b32_e32 v39, v164
	v_mov_b32_e32 v41, v166
	v_mov_b32_e32 v38, v168
	v_mov_b32_e32 v40, v170
	v_pk_add_f32 v[4:5], v[128:129], 1.0 op_sel_hi:[1,0]
	v_pk_add_f32 v[6:7], v[130:131], 1.0 op_sel_hi:[1,0]
	v_pk_fma_f32 v[4:5], v[34:35], v[4:5], v[124:125]
	v_pk_fma_f32 v[6:7], v[36:37], v[6:7], v[126:127]
	v_cvt_pk_bf16_f32 v4, v4, v5
	v_mov_b32_e32 v21, v165
	v_cvt_pk_bf16_f32 v5, v6, v7
	global_store_dwordx2 v[46:47], v[4:5], off offset:1536
	v_mov_b32_e32 v23, v167
	v_mov_b32_e32 v20, v169
	v_mov_b32_e32 v22, v171
	v_mov_b32_e32 v35, v172
	v_mov_b32_e32 v5, v173
	v_mov_b32_e32 v37, v174
	v_mov_b32_e32 v7, v175
	v_mov_b32_e32 v34, v176
	v_mov_b32_e32 v4, v177
	v_mov_b32_e32 v36, v178
	v_mov_b32_e32 v6, v179
	s_cbranch_vccz .Lln2a_exit
	s_branch .LBB0_1624
.Lln2a_topB:
	s_add_i32 s7, s6, s82
	s_cmpk_gt_i32 s7, 0x7fff
	s_cselect_b64 s[2:3], -1, 0
	s_add_i32 s10, s7, s82
	s_cmp_lt_i32 s10, 0x8000
	s_cselect_b32 s10, s10, s6
	s_ashr_i32 s11, s10, 31
	s_lshl_b64 s[10:11], s[10:11], 12
	v_lshl_add_u64 v[0:1], v[24:25], 0, s[10:11]
	s_add_i32 s101, s6, 0xffffc000
	s_lshr_b32 s101, s101, 12
	s_add_i32 s101, s101, 2
	s_ashr_i32 s100, s6, 13
	s_cmpk_lt_i32 s6, 0x4000
	s_cselect_b32 s100, s100, s101
	v_readlane_b32 s101, v255, 11
	s_nop 1
	s_add_i32 s100, s100, s101
	s_mul_i32 s100, s100, 9
	s_ashr_i32 s101, s100, 31
	s_lshl_b64 s[100:101], s[100:101], 12
	v_lshl_add_u64 v[60:61], v[30:31], 0, s[100:101]
	s_mov_b64 s[100:101], 0x6000
	v_lshl_add_u64 v[62:63], v[60:61], 0, s[100:101]
	s_mov_b64 s[100:101], 0x7000
	v_lshl_add_u64 v[64:65], v[60:61], 0, s[100:101]
	global_load_dwordx4 v[68:71], v[26:27], off
	global_load_dwordx4 v[72:75], v[28:29], off
	global_load_dwordx4 v[76:79], v[62:63], off
	global_load_dwordx4 v[80:83], v[64:65], off
	global_load_dwordx4 v[84:87], v[26:27], off offset:1024
	global_load_dwordx4 v[88:91], v[28:29], off offset:1024
	global_load_dwordx4 v[92:95], v[62:63], off offset:1024
	global_load_dwordx4 v[96:99], v[64:65], off offset:1024
	global_load_dwordx4 v[100:103], v[26:27], off offset:2048
	global_load_dwordx4 v[104:107], v[28:29], off offset:2048
	global_load_dwordx4 v[108:111], v[62:63], off offset:2048
	global_load_dwordx4 v[112:115], v[64:65], off offset:2048
	global_load_dwordx4 v[116:119], v[26:27], off offset:3072
	global_load_dwordx4 v[120:123], v[28:29], off offset:3072
	global_load_dwordx4 v[124:127], v[62:63], off offset:3072
	global_load_dwordx4 v[128:131], v[64:65], off offset:3072
	global_load_dwordx4 v[16:19], v[0:1], off
	global_load_dwordx4 v[12:15], v[0:1], off offset:1024
	global_load_dwordx4 v[8:11], v[0:1], off offset:2048
	s_nop 0
	global_load_dwordx4 v[0:3], v[0:1], off offset:3072
	v_pk_add_f32 v[42:43], v[38:39], v[20:21]
	s_mov_b32 s8, 0x800000
	v_pk_add_f32 v[42:43], v[40:41], v[42:43]
	s_nop 0
	v_pk_add_f32 v[42:43], v[22:23], v[42:43]
	s_nop 0
	v_add_f32_e32 v43, 0, v43
	v_add_f32_e32 v44, v42, v43
	v_pk_add_f32 v[42:43], v[34:35], v[4:5]
	s_nop 0
	v_pk_add_f32 v[42:43], v[36:37], v[42:43]
	s_nop 0
	v_pk_add_f32 v[42:43], v[6:7], v[42:43]
	s_nop 0
	v_add_f32_e32 v43, v43, v44
	v_add_f32_e32 v42, v42, v43
	s_nop 1
	v_add_f32_dpp v42, v42, v42 quad_perm:[1,0,3,2] row_mask:0xf bank_mask:0xf bound_ctrl:1
	s_nop 1
	v_add_f32_dpp v42, v42, v42 quad_perm:[2,3,0,1] row_mask:0xf bank_mask:0xf bound_ctrl:1
	s_nop 1
	v_add_f32_dpp v42, v42, v42 row_half_mirror row_mask:0xf bank_mask:0xf bound_ctrl:1
	s_nop 1
	v_add_f32_dpp v42, v42, v42 row_mirror row_mask:0xf bank_mask:0xf bound_ctrl:1
	s_nop 0
	v_readlane_b32 s12, v42, 16
	v_readlane_b32 s13, v42, 48
	v_readlane_b32 s10, v42, 0
	v_readlane_b32 s11, v42, 32
	v_mov_b32_e32 v42, s12
	v_mov_b32_e32 v43, s13
	v_pk_add_f32 v[42:43], s[10:11], v[42:43]
	s_nop 0
	v_add_f32_e32 v43, v42, v43
	v_fmac_f32_e32 v21, 0xba800000, v43
	v_fmac_f32_e32 v20, 0xba800000, v43
	v_fmac_f32_e32 v39, 0xba800000, v43
	v_fmac_f32_e32 v38, 0xba800000, v43
	v_mov_b32_e32 v46, v21
	v_mov_b32_e32 v47, v20
	v_fmac_f32_e32 v41, 0xba800000, v43
	v_fmac_f32_e32 v40, 0xba800000, v43
	v_mov_b32_e32 v44, v39
	v_mov_b32_e32 v45, v38
	v_pk_mul_f32 v[46:47], v[46:47], v[46:47]
	v_fmac_f32_e32 v23, 0xba800000, v43
	v_fmac_f32_e32 v22, 0xba800000, v43
	v_pk_fma_f32 v[44:45], v[44:45], v[44:45], v[46:47]
	v_mov_b32_e32 v46, v41
	v_mov_b32_e32 v47, v40
	v_pk_fma_f32 v[44:45], v[46:47], v[46:47], v[44:45]
	v_mov_b32_e32 v46, v23
	v_mov_b32_e32 v47, v22
	v_fmac_f32_e32 v5, 0xba800000, v43
	v_fmac_f32_e32 v4, 0xba800000, v43
	v_pk_fma_f32 v[44:45], v[46:47], v[46:47], v[44:45]
	v_fmac_f32_e32 v35, 0xba800000, v43
	v_fmac_f32_e32 v34, 0xba800000, v43
	v_pk_mul_f32 v[46:47], v[4:5], v[4:5]
	v_fmac_f32_e32 v37, 0xba800000, v43
	v_fmac_f32_e32 v36, 0xba800000, v43
	v_pk_fma_f32 v[46:47], v[34:35], v[34:35], v[46:47]
	v_fmac_f32_e32 v7, 0xba800000, v43
	v_fmac_f32_e32 v6, 0xba800000, v43
	v_pk_fma_f32 v[46:47], v[36:37], v[36:37], v[46:47]
	v_add_f32_e32 v42, v44, v45
	v_pk_fma_f32 v[46:47], v[6:7], v[6:7], v[46:47]
	s_nop 0
	v_add_f32_e32 v42, v47, v42
	v_add_f32_e32 v42, v46, v42
	s_nop 1
	v_add_f32_dpp v42, v42, v42 quad_perm:[1,0,3,2] row_mask:0xf bank_mask:0xf bound_ctrl:1
	s_nop 1
	v_add_f32_dpp v42, v42, v42 quad_perm:[2,3,0,1] row_mask:0xf bank_mask:0xf bound_ctrl:1
	s_nop 1
	v_add_f32_dpp v42, v42, v42 row_half_mirror row_mask:0xf bank_mask:0xf bound_ctrl:1
	s_nop 1
	v_add_f32_dpp v42, v42, v42 row_mirror row_mask:0xf bank_mask:0xf bound_ctrl:1
	s_nop 0
	v_readlane_b32 s12, v42, 16
	v_readlane_b32 s13, v42, 48
	v_readlane_b32 s10, v42, 0
	v_readlane_b32 s11, v42, 32
	v_mov_b32_e32 v44, s12
	v_mov_b32_e32 v45, s13
	v_pk_add_f32 v[44:45], s[10:11], v[44:45]
	s_nop 0
	v_add_f32_e32 v42, v44, v45
	v_fmamk_f32 v42, v42, 0x3a800000, v232
	v_mul_f32_e32 v44, 0x4b800000, v42
	v_cmp_gt_f32_e32 vcc, s8, v42
	s_nop 1
	v_cndmask_b32_e32 v42, v42, v44, vcc
	v_rsq_f32_e32 v42, v42
	s_nop 0
	v_mul_f32_e32 v44, 0x45800000, v42
	v_cndmask_b32_e32 v42, v42, v44, vcc
	s_and_saveexec_b64 s[12:13], s[38:39]
	s_cbranch_execz .LBB0_1623
	s_add_u32 s10, s92, s0
	v_mul_f32_e32 v44, 0x3a800000, v43
	s_addc_u32 s11, s93, s1
	v_mov_b32_e32 v45, v42
	global_store_dwordx2 v51, v[44:45], s[10:11]
	s_branch .Lln2a_outB
.Lln2a_exit:
	s_waitcnt vmcnt(0)
	s_branch .LBB0_1626
